# NA V-projection GEMM job: block rotation changed so the two jobs' extra tiles fall on different blocks
# speedup vs baseline: 1.0115x; 1.0003x over previous
; template <int EPI, int NB>
; DEVI void gemm_run(const GemmJob& J, unsigned char* smem, int rot) {
;   constexpr int BN = NB * 32;
;   const int G = gridDim.x;
;   int b = (int)blockIdx.x - rot; if (b < 0) b += G;
;   if (G & 7) {
;     const int ntiles = MT128 * J.ntn;
;     for (int t = b; t < ntiles; t += G) {
;       const int mt = t / J.ntn, nt = J.nt0 + (t - mt * J.ntn);
;       gemm_tile<EPI, NB>(J, mt * 128, nt * BN, smem);
;     }
;   } else {
;     const int x = b & 7, lb = b >> 3, nlb = G >> 3;
;     const int mlo = x * 49;
;     const int mcnt = min(49, MT128 - mlo);
;     const int ntot = mcnt * J.ntn, gsz = 8 * J.ntn;
;     const int ngrp = (mcnt + 7) >> 3;
.LBB0_144:
	s_ashr_i32 s4, s2, 31
	s_and_b32 s4, s4, s96
	s_add_i32 s14, s4, s2
	s_and_b32 s4, s96, 7
	s_cmp_lg_u32 s4, 0
	s_cselect_b64 s[18:19], -1, 0
	s_cmpk_lt_i32 s14, 0x216e
	s_cselect_b64 s[4:5], -1, 0
	s_and_b32 s9, s2, 7
	s_ashr_i32 s20, s96, 3
	v_writelane_b32 v252, s20, 1
	s_mul_i32 s20, s9, 49
	s_sub_i32 s9, 0x185, s20
	s_min_u32 s22, s9, 49
	s_ashr_i32 s15, s14, 3
	s_mul_i32 s9, s22, 22
	s_cmp_lt_i32 s15, s9
	v_writelane_b32 v252, s9, 2
	s_cselect_b64 s[24:25], -1, 0
	s_mul_i32 s8, s97, s96
	v_writelane_b32 v252, s24, 3
	s_mul_i32 s8, s8, s55
	s_mov_b64 s[10:11], 0xb286000
	v_writelane_b32 v252, s25, 4
	v_writelane_b32 v252, s8, 5
	s_add_u32 s8, s6, 0x1200
	s_addc_u32 s9, s7, 0
	v_writelane_b32 v252, s8, 6
	v_lshl_add_u64 v[152:153], v[130:131], 0, s[10:11]
	v_lshl_add_u64 v[158:159], v[148:149], 0, s[10:11]
	v_writelane_b32 v252, s9, 7
	s_add_u32 s8, s6, 0x1400
	s_addc_u32 s9, s7, 0
	v_writelane_b32 v252, s8, 8
	s_load_dwordx4 s[24:27], s[0:1], 0xb0
	s_load_dwordx8 s[68:75], s[0:1], 0x0
	v_writelane_b32 v252, s9, 9
	s_add_u32 s8, s6, 0x1500
	s_addc_u32 s9, s7, 0
	v_writelane_b32 v252, s8, 10
	s_mov_b64 s[12:13], 0x5000
	v_lshl_add_u64 v[150:151], v[130:131], 0, s[12:13]
	v_writelane_b32 v252, s9, 11
	s_add_u32 s8, s6, 0x1600
	s_addc_u32 s9, s7, 0
	v_writelane_b32 v252, s8, 12
	v_lshl_add_u64 v[166:167], v[148:149], 0, s[12:13]
	v_lshlrev_b32_e32 v188, 2, v177
	v_writelane_b32 v252, s9, 13
	s_add_u32 s8, s6, 0x1700
	s_addc_u32 s9, s7, 0
	v_writelane_b32 v252, s8, 14
	s_mov_b32 s21, 0
	v_or_b32_e32 v189, 0xf000, v188
	v_writelane_b32 v252, s9, 15
	s_add_u32 s8, s6, 0x1800
	s_addc_u32 s9, s7, 0
	v_writelane_b32 v252, s8, 16
	v_add_u32_e32 v190, 0xffffff00, v177
	v_cndmask_b32_e64 v192, 0, 1, s[4:5]
	v_writelane_b32 v252, s9, 17
	s_add_u32 s8, s6, 0x1900
	s_addc_u32 s9, s7, 0
	v_writelane_b32 v252, s8, 18
	v_mov_b32_e32 v1, 0
	s_mov_b64 s[30:31], 0x1000
	v_writelane_b32 v252, s9, 19
	s_add_u32 s8, s6, 0x1a00
	s_addc_u32 s9, s7, 0
	v_writelane_b32 v252, s8, 20
	s_mov_b64 s[94:95], 0x30a000
	s_mov_b64 s[50:51], 0x58000
	v_writelane_b32 v252, s9, 21
	s_add_u32 s8, s6, 0x1b00
	s_addc_u32 s9, s7, 0
	v_writelane_b32 v252, s8, 22
	s_mov_b64 s[84:85], 0x575a000
	s_mov_b32 s93, 0xc280
	v_writelane_b32 v252, s9, 23
	s_add_u32 s8, s6, 0x1c00
	s_addc_u32 s9, s7, 0
	v_writelane_b32 v252, s8, 24
	v_mov_b32_e32 v193, 0x12000
	v_mov_b32_e32 v194, 0x12004
	v_writelane_b32 v252, s9, 25
	s_add_u32 s8, s6, 0x1d00
	s_addc_u32 s9, s7, 0
	v_writelane_b32 v252, s8, 26
	v_mov_b32_e32 v195, 1
	s_mov_b64 s[4:5], 0x30000
	v_writelane_b32 v252, s9, 27
	s_add_u32 s8, s6, 0x1e00
	s_addc_u32 s9, s7, 0
	v_writelane_b32 v252, s8, 28
	v_mov_b32_e32 v196, 0x11f80
	s_mov_b32 s92, 0x3e38aa3b
	v_writelane_b32 v252, s9, 29
	s_add_u32 s8, s6, 0x1f00
	s_addc_u32 s9, s7, 0
	v_writelane_b32 v252, s8, 30
	s_mov_b64 s[38:39], 0x18000
	s_mov_b64 s[86:87], 0xc000
	v_writelane_b32 v252, s9, 31
	s_add_u32 s8, s6, 0x2000
	s_addc_u32 s9, s7, 0
	v_writelane_b32 v252, s8, 32
	s_mov_b32 s34, 0x3e16c740
	s_mov_b64 s[36:37], 0x12d6000
	v_writelane_b32 v252, s9, 33
	s_add_u32 s8, s6, 0x2100
	s_addc_u32 s9, s7, 0
	v_writelane_b32 v252, s8, 34
	s_mov_b64 s[88:89], 0x12d8000
	s_mov_b64 s[90:91], 0x12d9000
	v_writelane_b32 v252, s9, 35
	s_add_u32 s8, s6, 0x2200
	s_addc_u32 s9, s7, 0
	v_writelane_b32 v252, s8, 36
	v_mov_b32_e32 v197, 0x2100000
	v_mov_b32_e32 v198, 0x61400
	v_writelane_b32 v252, s9, 37
	s_add_u32 s8, s6, 0x2300
	s_addc_u32 s9, s7, 0
	v_writelane_b32 v252, s8, 38
	s_cmp_eq_u32 s54, 15
	v_mov_b32_e32 v199, 0xc2800
	v_writelane_b32 v252, s9, 39
	s_cselect_b64 s[8:9], -1, 0
	v_writelane_b32 v252, s8, 40
	s_cmp_eq_u32 s54, 14
	v_mov_b32_e32 v200, 0x123c00
	v_writelane_b32 v252, s9, 41
	s_cselect_b64 s[8:9], -1, 0
	v_writelane_b32 v252, s8, 42
	s_cmp_eq_u32 s54, 13
	v_mov_b32_e32 v201, 0xffffdfc0
	v_writelane_b32 v252, s9, 43
	s_cselect_b64 s[8:9], -1, 0
	v_writelane_b32 v252, s8, 44
	s_cmp_eq_u32 s54, 12
	v_mov_b32_e32 v202, 0xffff8000
	v_writelane_b32 v252, s9, 45
	s_cselect_b64 s[8:9], -1, 0
	v_writelane_b32 v252, s8, 46
	s_cmp_eq_u32 s54, 11
	v_mbcnt_hi_u32_b32 v203, -1, v51
	v_writelane_b32 v252, s9, 47
	s_cselect_b64 s[8:9], -1, 0
	v_writelane_b32 v252, s8, 48
	s_cmp_eq_u32 s54, 10
	v_mov_b32_e32 v204, 0xf149f2ca
	v_writelane_b32 v252, s9, 49
	s_cselect_b64 s[8:9], -1, 0
	v_writelane_b32 v252, s8, 50
	s_cmp_eq_u32 s54, 9
	v_mov_b32_e32 v205, 0x840
	v_writelane_b32 v252, s9, 51
	s_cselect_b64 s[8:9], -1, 0
	v_writelane_b32 v252, s8, 52
	s_cmp_eq_u32 s54, 8
	v_mov_b32_e32 v206, 0xc280
	v_writelane_b32 v252, s9, 53
	s_cselect_b64 s[8:9], -1, 0
	v_writelane_b32 v252, s8, 54
	s_cmp_eq_u32 s54, 7
	v_mov_b32_e32 v207, 0x600
	v_writelane_b32 v252, s9, 55
	s_cselect_b64 s[8:9], -1, 0
	v_writelane_b32 v252, s8, 56
	s_cmp_eq_u32 s54, 6
	v_mov_b32_e32 v176, 0x358637bd
	v_writelane_b32 v252, s9, 57
	s_cselect_b64 s[8:9], -1, 0
	v_writelane_b32 v252, s8, 58
	s_cmp_eq_u32 s54, 5
	s_nop 0
	v_writelane_b32 v252, s9, 59
	s_cselect_b64 s[8:9], -1, 0
	v_writelane_b32 v252, s8, 60
	s_cmp_eq_u32 s54, 4
	s_nop 0
	v_writelane_b32 v252, s9, 61
	s_cselect_b64 s[8:9], -1, 0
	v_writelane_b32 v252, s8, 62
	s_cmp_eq_u32 s54, 3
	s_nop 0
	v_writelane_b32 v252, s9, 63
	s_cselect_b64 s[8:9], -1, 0
	v_writelane_b32 v251, s8, 0
	s_cmp_eq_u32 s54, 2
	s_nop 0
	v_writelane_b32 v251, s9, 1
	s_cselect_b64 s[8:9], -1, 0
	v_writelane_b32 v251, s8, 2
	s_cmp_eq_u32 s54, 1
	s_nop 0
	v_writelane_b32 v251, s9, 3
	s_cselect_b64 s[8:9], -1, 0
	v_writelane_b32 v251, s8, 4
	s_cmp_eq_u32 s54, 0
	s_nop 0
	v_writelane_b32 v251, s9, 5
	s_cselect_b64 s[8:9], -1, 0
	v_writelane_b32 v251, s8, 6
	s_nop 1
	v_writelane_b32 v251, s9, 7
; template <int EPI, int NB>
; DEVI void gemm_run(const GemmJob& J, unsigned char* smem, int rot) {
;   constexpr int BN = NB * 32;
;   const int G = gridDim.x;
;   int b = (int)blockIdx.x - rot; if (b < 0) b += G;
;   if (G & 7) {
;     const int ntiles = MT128 * J.ntn;
;     for (int t = b; t < ntiles; t += G) {
;       const int mt = t / J.ntn, nt = J.nt0 + (t - mt * J.ntn);
;       gemm_tile<EPI, NB>(J, mt * 128, nt * BN, smem);
;     }
;   } else {
;     const int x = b & 7, lb = b >> 3, nlb = G >> 3;
;     const int mlo = x * 49;
;     const int mcnt = min(49, MT128 - mlo);
;     const int ntot = mcnt * J.ntn, gsz = 8 * J.ntn;
;     const int ngrp = (mcnt + 7) >> 3;
; DEVI void attn_na_phase(const Params& p, unsigned char* smem, unsigned* ctr) {
;     ...
;     for (int i = threadIdx.x; i < 465; i += 256) biasL[i] = p.na_rpb[h * 465 + i] * LOG2E;
;     if (threadIdx.x < 16) biasL[480 + threadIdx.x] = p.na_meta_bias[h * 16 + threadIdx.x] * LOG2E;
;     AttnArgs a;
;     a.Lr = Lr; a.Lk = Lk; a.sc2 = 0.125f * LOG2E;
;     a.K = Hb + H_NAQK + (size_t)kb * 2048 + 1024 + h * 64; a.ldk = 2048;
	s_lshl_b32 s8, s54, 8
	s_add_u32 s8, s16, s8
	s_addc_u32 s9, s17, 0
	s_add_u32 s16, s8, 0x1400
	s_addc_u32 s17, s9, 0
	v_writelane_b32 v251, s16, 8
	s_add_u32 s8, s8, 0x2400
	s_addc_u32 s9, s9, 0
	v_writelane_b32 v251, s17, 9
	v_writelane_b32 v251, s8, 10
	s_nop 1
	v_writelane_b32 v251, s9, 11
	s_add_u32 s8, s6, 0x4400
	s_addc_u32 s9, s7, 0
	v_writelane_b32 v251, s8, 12
	s_add_u32 s6, s6, 0x4500
	s_addc_u32 s7, s7, 0
	v_writelane_b32 v251, s9, 13
	v_writelane_b32 v251, s6, 14
	s_cmpk_lt_i32 s14, 0x614
	s_mov_b64 s[8:9], 0x5146000
	v_writelane_b32 v251, s7, 15
	s_cselect_b64 s[6:7], -1, 0
	s_lshl_b32 s16, s22, 2
	v_writelane_b32 v251, s6, 16
	s_cmp_lt_i32 s15, s16
	v_lshl_add_u64 v[160:161], v[148:149], 0, s[8:9]
	v_writelane_b32 v251, s7, 17
	s_cselect_b64 s[6:7], -1, 0
	v_writelane_b32 v251, s6, 18
	s_cmpk_lt_i32 s14, 0xc28
	s_movk_i32 s8, 0x1d1
	v_writelane_b32 v251, s7, 19
	s_mov_b64 s[6:7], 0x106000
	v_lshl_add_u64 v[154:155], v[148:149], 0, s[6:7]
	s_cselect_b64 s[6:7], -1, 0
	v_writelane_b32 v251, s6, 20
	v_cmp_gt_u32_e64 s[8:9], s8, v177
	s_nop 0
	v_writelane_b32 v251, s7, 21
	s_lshl_b32 s6, s22, 3
	s_cmp_lt_i32 s15, s6
	v_writelane_b32 v251, s6, 22
	s_cselect_b64 s[6:7], -1, 0
	v_writelane_b32 v251, s6, 23
	s_cmpk_lt_i32 s14, 0x799
	s_nop 0
	v_writelane_b32 v251, s7, 24
	v_writelane_b32 v251, s8, 25
	s_mov_b64 s[6:7], 0x17506000
	v_lshl_add_u64 v[156:157], v[130:131], 0, s[6:7]
	v_writelane_b32 v251, s9, 26
	v_cmp_gt_u32_e64 s[8:9], 16, v177
	v_lshl_add_u64 v[162:163], v[148:149], 0, s[6:7]
	s_cselect_b64 s[6:7], -1, 0
	v_writelane_b32 v251, s8, 27
	s_nop 1
	v_writelane_b32 v251, s9, 28
	s_load_dwordx4 s[8:11], s[0:1], 0x98
	s_waitcnt lgkmcnt(0)
	v_writelane_b32 v251, s8, 29
	s_nop 1
	v_writelane_b32 v251, s9, 30
	v_writelane_b32 v251, s10, 31
	v_writelane_b32 v251, s11, 32
	v_writelane_b32 v251, s6, 33
	s_load_dwordx4 s[8:11], s[0:1], 0x78
	s_nop 0
	v_writelane_b32 v251, s7, 34
	s_mul_i32 s6, s22, 5
	s_cmp_lt_i32 s15, s6
	v_writelane_b32 v251, s6, 35
	s_cselect_b64 s[6:7], -1, 0
	v_writelane_b32 v251, s6, 36
	s_cmpk_lt_i32 s14, 0x48f
	s_nop 0
	v_writelane_b32 v251, s7, 37
	s_mov_b64 s[6:7], 0x1d950000
	v_lshl_add_u64 v[164:165], v[130:131], 0, s[6:7]
	s_load_dwordx2 s[6:7], s[0:1], 0x58
	s_waitcnt lgkmcnt(0)
	v_writelane_b32 v251, s6, 38
	s_nop 1
	v_writelane_b32 v251, s7, 39
	s_load_dwordx2 s[6:7], s[0:1], 0x68
	s_mov_b64 s[0:1], 0x116d0000
	v_lshl_add_u64 v[168:169], v[130:131], 0, s[0:1]
	s_cselect_b64 s[0:1], -1, 0
	s_waitcnt lgkmcnt(0)
; template <int EPI, int NB>
; DEVI void gemm_run(const GemmJob& J, unsigned char* smem, int rot) {
;   constexpr int BN = NB * 32;
;   const int G = gridDim.x;
;   int b = (int)blockIdx.x - rot; if (b < 0) b += G;
;   if (G & 7) {
;     const int ntiles = MT128 * J.ntn;
;     for (int t = b; t < ntiles; t += G) {
;       const int mt = t / J.ntn, nt = J.nt0 + (t - mt * J.ntn);
;       gemm_tile<EPI, NB>(J, mt * 128, nt * BN, smem);
;     }
;   } else {
;     const int x = b & 7, lb = b >> 3, nlb = G >> 3;
;     const int mlo = x * 49;
;     const int mcnt = min(49, MT128 - mlo);
;     const int ntot = mcnt * J.ntn, gsz = 8 * J.ntn;
;     const int ngrp = (mcnt + 7) >> 3;
; __global__ void __launch_bounds__(256, 2) fwd_megakernel(Params p) {
;     ...
;       {
;         GemmJob J{}; J.A = Ab; J.lda = DM; J.Bt = Wb + W_NAQKV_OFF; J.K = DM; J.NR = 3072; J.ablk = 1; J.nt0 = 0; J.ntn = 8; J.C = Hb + H_NAQK; J.ldc = 2048; J.nvalid = 2048;
;         gemm_run<1, 8>(J, smem, 0);
;         GemmJob V{}; V.A = Ab; V.lda = DM; V.Bt = Wb + W_NAQKV_OFF; V.K = DM; V.NR = 3072; V.ablk = 1; V.nt0 = 8; V.ntn = 4; V.C = Hb + H_VTN; V.nfirst = 2048; V.vrows = 1024;
;         gemm_run<2, 8>(V, smem, (MT128 * 8) % G);
;       }
	v_writelane_b32 v251, s6, 40
	s_nop 1
	v_writelane_b32 v251, s7, 41
	v_writelane_b32 v251, s8, 42
	s_nop 1
	v_writelane_b32 v251, s9, 43
	v_writelane_b32 v251, s10, 44
	v_writelane_b32 v251, s11, 45
	v_writelane_b32 v251, s0, 46
	s_nop 1
	v_writelane_b32 v251, s1, 47
	s_mul_i32 s0, s22, 3
	v_writelane_b32 v251, s22, 48
	s_cmp_lt_i32 s15, s0
	v_writelane_b32 v251, s0, 49
	s_cselect_b64 s[0:1], -1, 0
	v_writelane_b32 v251, s0, 50
	s_nop 1
	v_writelane_b32 v251, s1, 51
	s_mov_b64 s[0:1], 0xb286200
	v_lshl_add_u64 v[170:171], v[130:131], 0, s[0:1]
	s_mov_b64 s[0:1], 0x15fc0000
	v_lshl_add_u64 v[172:173], v[130:131], 0, s[0:1]
	s_mov_b64 s[0:1], 0x1a8b0000
	v_lshl_add_u64 v[174:175], v[130:131], 0, s[0:1]
	s_add_u32 s0, s26, 0xb286000
	v_writelane_b32 v251, s0, 52
	s_addc_u32 s0, s27, 0
	v_writelane_b32 v251, s0, 53
	s_add_u32 s0, s26, 0x5146000
	s_addc_u32 s1, s27, 0
	v_writelane_b32 v251, s0, 54
	s_nop 1
	v_writelane_b32 v251, s1, 55
	s_add_u32 s0, s26, 0x1d950000
	v_writelane_b32 v251, s0, 56
	s_addc_u32 s0, s27, 0
	v_writelane_b32 v251, s0, 57
	s_add_u32 s0, s26, 0x116d0000
	v_writelane_b32 v251, s0, 58
	s_addc_u32 s0, s27, 0
	v_writelane_b32 v251, s0, 59
	s_add_u32 s0, s26, 0x15fc0000
	v_writelane_b32 v251, s0, 60
	s_addc_u32 s0, s27, 0
	v_writelane_b32 v251, s0, 61
	s_add_u32 s0, s26, 0x1a8b0000
	v_writelane_b32 v251, s0, 62
	s_addc_u32 s0, s27, 0
	v_writelane_b32 v251, s0, 63
	s_add_u32 s0, s26, 0x106000
	v_writelane_b32 v250, s0, 0
	v_writelane_b32 v250, s24, 1
	s_addc_u32 s0, s27, 0
	s_nop 0
	v_writelane_b32 v250, s25, 2
	v_writelane_b32 v250, s26, 3
	v_writelane_b32 v250, s27, 4
	v_writelane_b32 v250, s0, 5
	s_mul_hi_u32 s0, s33, 64
	s_mul_i32 s0, s0, s3
	s_sub_i32 s0, 64, s0
	s_sub_i32 s1, s0, s3
	s_cmp_ge_u32 s0, s3
	s_cselect_b32 s0, s1, s0
	s_sub_i32 s1, s0, s3
	s_cmp_ge_u32 s0, s3
	s_cselect_b32 s0, s1, s0
	s_sub_i32 s0, s2, s0
	s_ashr_i32 s1, s0, 31
	s_and_b32 s1, s1, s96
	s_add_i32 s7, s1, s0
	s_cmpk_lt_i32 s7, 0x614
	s_cselect_b64 s[0:1], -1, 0
	s_ashr_i32 s8, s7, 3
	v_writelane_b32 v250, s0, 6
	s_cmp_lt_i32 s8, s16
	s_mov_b64 s[24:25], 0xb89a000
	v_writelane_b32 v250, s1, 7
	s_cselect_b64 s[0:1], -1, 0
	v_writelane_b32 v250, s0, 8
	s_mov_b64 s[26:27], 0xb89b000
	s_nop 0
	v_writelane_b32 v250, s1, 9
	s_mul_hi_u32 s0, s33, 0x799
	s_mul_i32 s0, s0, s3
	s_sub_i32 s0, 0x799, s0
	s_sub_i32 s1, s0, s3
	s_cmp_ge_u32 s0, s3
	s_cselect_b32 s0, s1, s0
	s_sub_i32 s1, s0, s3
	s_cmp_ge_u32 s0, s3
	s_cselect_b32 s0, s1, s0
	s_sub_i32 s0, s2, s0
	s_ashr_i32 s1, s0, 31
	s_and_b32 s1, s1, s96
	s_add_i32 s9, s1, s0
	s_cmpk_lt_i32 s9, 0x185
	s_cselect_b64 s[10:11], -1, 0
	v_writelane_b32 v250, s10, 10
	s_and_b32 s0, s0, 7
	s_nop 0
	v_writelane_b32 v250, s11, 11
	s_mul_i32 s11, s0, 49
	s_sub_i32 s1, 0x185, s11
	s_ashr_i32 s10, s9, 3
	s_min_u32 s12, s1, 49
	s_mul_hi_u32 s1, s33, 0x48f
	s_cmp_lt_i32 s10, s12
	s_mul_i32 s1, s1, s3
	s_cselect_b64 s[22:23], -1, 0
	s_sub_i32 s1, 0x48f, s1
	s_sub_i32 s6, s1, s3
	s_cmp_ge_u32 s1, s3
	s_cselect_b32 s1, s6, s1
	s_sub_i32 s6, s1, s3
	s_cmp_ge_u32 s1, s3
	s_cselect_b32 s1, s6, s1
	s_sub_i32 s1, s2, s1
	s_ashr_i32 s3, s1, 31
	s_and_b32 s3, s3, s96
	s_add_i32 s6, s3, s1
	v_writelane_b32 v250, s22, 12
	s_cmpk_lt_i32 s6, 0x30a
	s_mulk_i32 s0, 0x1880
	v_writelane_b32 v250, s23, 13
	s_cselect_b64 s[22:23], -1, 0
	s_and_b32 s1, s1, 7
	s_mul_i32 s17, s1, 49
	v_writelane_b32 v250, s22, 14
	s_sub_i32 s1, 0x185, s17
	s_min_u32 s1, s1, 49
	v_writelane_b32 v250, s23, 15
	s_ashr_i32 s13, s6, 3
	v_writelane_b32 v250, s1, 16
	s_lshl_b32 s1, s1, 1
	s_cmp_lt_i32 s13, s1
	v_writelane_b32 v250, s1, 17
	s_cselect_b64 s[22:23], -1, 0
	v_writelane_b32 v250, s22, 18
	s_cmpk_lt_i32 s9, 0x30a
	s_movk_i32 s33, 0x400
	v_writelane_b32 v250, s23, 19
	s_cselect_b64 s[22:23], -1, 0
	v_writelane_b32 v250, s22, 20
	s_lshl_b32 s1, s12, 1
	s_cmp_lt_i32 s10, s1
	v_writelane_b32 v250, s23, 21
	v_writelane_b32 v250, s12, 22
	v_writelane_b32 v250, s1, 23
	s_cselect_b64 s[22:23], -1, 0
	v_writelane_b32 v250, s22, 24
	s_lshl_b32 s1, s14, 8
	s_not_b32 s3, s15
	v_writelane_b32 v250, s23, 25
	v_writelane_b32 v250, s14, 26
	v_writelane_b32 v250, s1, 27
	s_lshl_b32 s1, s96, 8
	v_writelane_b32 v250, s1, 28
	s_add_i32 s1, s15, s20
	v_writelane_b32 v250, s1, 29
	v_writelane_b32 v250, s16, 30
	s_add_i32 s1, s20, s16
	v_writelane_b32 v250, s15, 31
	s_add_i32 s1, s3, s1
	v_writelane_b32 v250, s1, 32
	s_lshl_b32 s1, s2, 3
	v_writelane_b32 v250, s1, 33
	s_lshl_b32 s1, s96, 3
	v_writelane_b32 v250, s1, 34
	s_lshl_b32 s1, s7, 8
	v_writelane_b32 v250, s7, 35
	s_addk_i32 s1, 0x800
	v_writelane_b32 v250, s1, 36
	v_writelane_b32 v250, s20, 37
	v_writelane_b32 v250, s8, 38
	s_add_i32 s1, s8, s20
	v_writelane_b32 v250, s1, 39
	s_lshl_b32 s1, s9, 7
	v_writelane_b32 v250, s1, 40
	s_lshl_b32 s1, s96, 7
	v_writelane_b32 v250, s1, 41
	s_lshl_b32 s1, s10, 7
	s_add_i32 s0, s0, s1
	v_writelane_b32 v250, s0, 42
	s_lshl_b32 s0, s96, 4
	v_writelane_b32 v250, s0, 43
	v_readlane_b32 s0, v252, 0
	s_add_i32 s0, s0, 0xffff7e00
	s_mov_b64 s[22:23], 0x10000
	v_writelane_b32 v250, s0, 44
	v_writelane_b32 v250, s6, 45
	s_lshl_b32 s0, s6, 8
	v_writelane_b32 v250, s0, 46
	v_writelane_b32 v250, s13, 47
	v_writelane_b32 v250, s17, 48
	s_add_i32 s0, s13, s17
	v_writelane_b32 v250, s0, 49
	s_lshl_b32 s0, s9, 8
	v_writelane_b32 v250, s9, 50
	s_addk_i32 s0, 0x200
	v_writelane_b32 v250, s0, 51
	v_writelane_b32 v250, s10, 52
	v_writelane_b32 v250, s11, 53
	s_add_i32 s0, s10, s11
	v_writelane_b32 v250, s0, 54
	s_mov_b64 s[0:1], -1
	v_writelane_b32 v250, s0, 55
	s_mov_b64 s[12:13], 0x575b000
	s_mov_b64 s[6:7], 0x12d7000
	v_writelane_b32 v250, s1, 56
	v_writelane_b32 v250, s18, 57
	s_mov_b64 s[10:11], 0x1d46000
	s_mov_b64 s[14:15], 0x1d47000
	v_writelane_b32 v250, s19, 58
	v_writelane_b32 v250, s68, 59
	v_cndmask_b32_e64 v191, 0, 1, s[18:19]
	s_mov_b64 s[16:17], 0x1d48000
	v_writelane_b32 v250, s69, 60
	v_writelane_b32 v250, s70, 61
	v_writelane_b32 v249, s73, 0
	s_mov_b64 s[18:19], 0x1d49000
	s_mov_b32 s8, 0
	v_writelane_b32 v250, s71, 62
	v_writelane_b32 v249, s74, 1
	v_writelane_b32 v250, s72, 63
	v_writelane_b32 v249, s75, 2
	s_branch .LBB0_148
